# flag barrier after the placement census: own-word arrival flags polled by a fixed XCD leader, per-XCD done words polled directly on global seams (write-through stores, no read-modify-write on the arri
# speedup vs baseline: 1.0060x; 1.0022x over previous
; __device__ __forceinline__ unsigned xb_ld(unsigned* p)              { return __hip_atomic_load(p, __ATOMIC_RELAXED, __HIP_MEMORY_SCOPE_AGENT); }
; __device__ __forceinline__ unsigned xb_add(unsigned* p, unsigned v) { return __hip_atomic_fetch_add(p, v, __ATOMIC_RELAXED, __HIP_MEMORY_SCOPE_AGENT); }
; #define XB_SPIN(cond, bar) do { unsigned _sp = 0; while (cond) { __builtin_amdgcn_s_sleep(1); \
;     if ((++_sp & 255u) == 0u) { if (xb_ld(&(bar)[XB_TMO])) break; if (_sp > XB_SPIN_CAP) { atomicAdd(&(bar)[XB_TMO], 1u); break; } } } } while (0)
; __device__ __forceinline__ void xcd_barrier(const XcdBarrier& b) {
;     asm volatile("s_waitcnt vmcnt(0)" ::: "memory");
;     __syncthreads();
;     if (threadIdx.x == 0) {
;         unsigned* bar = b.bar;
;         __builtin_amdgcn_s_waitcnt(0);
;         unsigned nloc = b.st[0], nx = b.st[1];
;         if (nloc == 0u) { xcd_barrier_complete(bar, b.x, nloc, nx); b.st[0] = nloc; b.st[1] = nx; }
;         const unsigned old = xb_add(&bar[XB_XSUB(b.x)], 1u);
;         const unsigned gen = old / nloc;
;         if (old + 1u == (gen + 1u) * nloc) {
;             __builtin_amdgcn_fence(__ATOMIC_RELEASE, "agent");
;             asm volatile("s_waitcnt vmcnt(0)" ::: "memory");
;             const unsigned og = xb_add(&bar[XB_TOP], 1u);
;             const unsigned tg = og / nx;
;             if (og + 1u == (tg + 1u) * nx) xb_add(&bar[XB_TOPGEN], 1u);
;             else XB_SPIN(xb_ld(&bar[XB_TOPGEN]) == tg, bar);
;             __builtin_amdgcn_fence(__ATOMIC_ACQUIRE, "agent");
;             xb_add(&bar[XB_XGEN(b.x)], 1u);
;             asm volatile("s_waitcnt vmcnt(0)" ::: "memory");
;         } else {
;             XB_SPIN(xb_ld(&bar[XB_XGEN(b.x)]) == gen, bar);
;             __builtin_amdgcn_fence(__ATOMIC_ACQUIRE, "agent");
;             asm volatile("s_waitcnt vmcnt(0)" ::: "memory");
;         }
;     }
;     __syncthreads();
; }
.Ltg_done:
	s_cmp_eq_u32 s101, 0
	s_cbranch_scc1 .Lfb_skip
	s_cmp_lt_i32 s97, 1
	s_cbranch_scc1 .Lfb_skip
	s_add_i32 s2, s97, 1
	s_lshl_b32 s2, s2, 4
	s_add_i32 s2, s2, 0x10000
	s_and_b32 s5, s27, 7
	s_lshr_b32 s6, s27, 3
	v_readlane_b32 s8, v254, 40
	v_readlane_b32 s9, v254, 41
	s_lshl_b32 s10, s5, 8
	s_lshl_b32 s11, s6, 2
	s_add_i32 s10, s10, s11
	s_addk_i32 s10, 0x1a00
	v_mov_b32_e32 v0, s10
	v_mov_b32_e32 v1, s2
	s_waitcnt vmcnt(0) lgkmcnt(0)
	global_store_dword v0, v1, s[8:9] sc1
	buffer_inv sc1
	s_mov_b32 s11, 0
	s_cmp_lg_u32 s6, 0
	s_cbranch_scc1 .Lfb_wait
	s_mov_b64 s[12:13], exec
	s_mov_b32 exec_lo, -1
	s_mov_b32 exec_hi, 0
	v_mbcnt_lo_u32_b32 v2, -1, 0
	v_lshlrev_b32_e32 v2, 2, v2
	s_lshl_b32 s10, s5, 8
	s_addk_i32 s10, 0x1a00
	v_add_u32_e32 v2, s10, v2
.Lfb_lpoll:
	global_load_dword v3, v2, s[8:9] sc1
	s_waitcnt vmcnt(0)
	v_cmp_gt_u32_e32 vcc, s2, v3
	s_cbranch_vccz .Lfb_lall
	s_sleep 1
	s_add_i32 s11, s11, 1
	s_cmp_lt_u32 s11, 0x8000
	s_cbranch_scc1 .Lfb_lpoll
.Lfb_lall:
	s_mov_b64 exec, s[12:13]
	s_cmp_lt_i32 s100, 0
	s_cbranch_scc1 .Lfb_ldone
	buffer_wbl2 sc1
	s_waitcnt vmcnt(0)
.Lfb_ldone:
	s_lshl_b32 s10, s5, 8
	s_addk_i32 s10, 0x2a00
	v_mov_b32_e32 v0, s10
	s_nop 0
	global_store_dword v0, v1, s[8:9] sc1
	s_cmp_lt_i32 s100, 0
	s_cbranch_scc1 .Lfb_exit
.Lfb_wait:
	s_mov_b64 s[12:13], exec
	s_cmp_lt_i32 s100, 0
	s_cbranch_scc1 .Lfb_wait_local
	s_mov_b32 exec_lo, 0xff
	s_mov_b32 exec_hi, 0
	v_mbcnt_lo_u32_b32 v2, -1, 0
	v_lshlrev_b32_e32 v2, 8, v2
	v_add_u32_e32 v2, 0x2a00, v2
	s_branch .Lfb_gpoll
.Lfb_wait_local:
	s_lshl_b32 s10, s5, 8
	s_addk_i32 s10, 0x2a00
	v_mov_b32_e32 v2, s10

; __device__ __forceinline__ void xcd_barrier(const XcdBarrier& b) {
;     ...
;     }
;     __syncthreads();
; }
.Lfb_gall:
	s_mov_b64 exec, s[12:13]
.Lfb_exit:
	s_waitcnt vmcnt(0)
	s_branch .LBB0_9
